# v13 + attention latch vmcnt(4) removed, spatial staging waits vmcnt(19) when the next V tile was prefetched
# speedup vs baseline: 1.0220x; 1.0147x over previous
.LBB0_320:
	s_or_b64 exec, exec, s[48:49]
	s_addk_i32 s77, 0x80
	s_add_i32 s54, s54, 1
	s_waitcnt vmcnt(5)
	v_mov_b64_e32 v[38:39], v[26:27]
	v_mov_b64_e32 v[34:35], v[22:23]
	v_lshl_add_u64 v[78:79], v[78:79], 0, s[88:89]
	v_lshl_add_u64 v[80:81], v[80:81], 0, s[88:89]
	v_lshl_add_u64 v[82:83], v[82:83], 0, s[88:89]
	v_lshl_add_u64 v[84:85], v[84:85], 0, s[88:89]
	s_cmpk_eq_i32 s77, 0x400
	v_mov_b64_e32 v[36:37], v[24:25]
	v_mov_b64_e32 v[32:33], v[20:21]
	s_cbranch_scc1 .LBB0_311

.LBB0_536:
	s_or_b64 exec, exec, s[82:83]
	ds_read_b32 v85, v204
	ds_read_b32 v84, v205
	s_waitcnt vmcnt(11)
	v_lshlrev_b32_e32 v88, 16, v32
	v_and_b32_e32 v89, 0xffff0000, v32
	v_lshlrev_b32_e32 v86, 16, v33
	v_and_b32_e32 v87, 0xffff0000, v33
	v_lshlrev_b32_e32 v92, 16, v34
	v_and_b32_e32 v93, 0xffff0000, v34
	v_lshlrev_b32_e32 v90, 16, v35
	v_and_b32_e32 v91, 0xffff0000, v35
	s_waitcnt lgkmcnt(1)
	v_sub_f32_e32 v87, v87, v85
	v_sub_f32_e32 v86, v86, v85
	v_sub_f32_e32 v89, v89, v85
	v_sub_f32_e32 v88, v88, v85
	v_sub_f32_e32 v91, v91, v85
	v_sub_f32_e32 v90, v90, v85
	v_sub_f32_e32 v93, v93, v85
	v_sub_f32_e32 v92, v92, v85
	s_waitcnt lgkmcnt(0)
	v_pk_mul_f32 v[88:89], v[84:85], v[88:89] op_sel_hi:[0,1]
	v_pk_mul_f32 v[86:87], v[84:85], v[86:87] op_sel_hi:[0,1]
	v_pk_mul_f32 v[92:93], v[84:85], v[92:93] op_sel_hi:[0,1]
	v_pk_mul_f32 v[84:85], v[84:85], v[90:91] op_sel_hi:[0,1]
	s_waitcnt vmcnt(0)
	v_pk_fma_f32 v[86:87], v[74:75], v[86:87], v[82:83]
	v_pk_fma_f32 v[88:89], v[72:73], v[88:89], v[80:81]
	v_pk_fma_f32 v[90:91], v[70:71], v[84:85], v[78:79]
	v_pk_fma_f32 v[92:93], v[68:69], v[92:93], v[76:77]
	v_cvt_pk_bf16_f32 v84, v88, v89
	v_cvt_pk_bf16_f32 v85, v86, v87
	v_cvt_pk_bf16_f32 v86, v92, v93
	v_cvt_pk_bf16_f32 v87, v90, v91
	v_add_u32_e32 v195, v202, v206
	ds_write_b128 v195, v[84:87] offset:34816
	ds_read_b32 v85, v207
	ds_read_b32 v84, v208
	v_lshlrev_b32_e32 v88, 16, v40
	v_and_b32_e32 v89, 0xffff0000, v40
	v_lshlrev_b32_e32 v86, 16, v41
	v_and_b32_e32 v87, 0xffff0000, v41
	v_lshlrev_b32_e32 v92, 16, v42
	v_and_b32_e32 v93, 0xffff0000, v42
	v_lshlrev_b32_e32 v90, 16, v43
	v_and_b32_e32 v91, 0xffff0000, v43
	s_waitcnt lgkmcnt(1)
	v_sub_f32_e32 v87, v87, v85
	v_sub_f32_e32 v86, v86, v85
	v_sub_f32_e32 v89, v89, v85
	v_sub_f32_e32 v88, v88, v85
	v_sub_f32_e32 v91, v91, v85
	v_sub_f32_e32 v90, v90, v85
	v_sub_f32_e32 v93, v93, v85
	v_sub_f32_e32 v92, v92, v85
	s_waitcnt lgkmcnt(0)
	v_pk_mul_f32 v[88:89], v[84:85], v[88:89] op_sel_hi:[0,1]
	v_pk_mul_f32 v[86:87], v[84:85], v[86:87] op_sel_hi:[0,1]
	v_pk_mul_f32 v[92:93], v[84:85], v[92:93] op_sel_hi:[0,1]
	v_pk_mul_f32 v[84:85], v[84:85], v[90:91] op_sel_hi:[0,1]
	v_pk_fma_f32 v[86:87], v[74:75], v[86:87], v[82:83]
	v_pk_fma_f32 v[88:89], v[72:73], v[88:89], v[80:81]
	v_pk_fma_f32 v[90:91], v[70:71], v[84:85], v[78:79]
	v_pk_fma_f32 v[92:93], v[68:69], v[92:93], v[76:77]
	v_cvt_pk_bf16_f32 v84, v88, v89
	v_cvt_pk_bf16_f32 v85, v86, v87
	v_cvt_pk_bf16_f32 v86, v92, v93
	v_cvt_pk_bf16_f32 v87, v90, v91
	ds_write_b128 v195, v[84:87] offset:43264
	ds_read_b32 v85, v209
	ds_read_b32 v84, v210
	v_lshlrev_b32_e32 v88, 16, v44
	v_and_b32_e32 v89, 0xffff0000, v44
	v_lshlrev_b32_e32 v86, 16, v45
	v_and_b32_e32 v87, 0xffff0000, v45
	v_lshlrev_b32_e32 v92, 16, v46
	v_and_b32_e32 v93, 0xffff0000, v46
	v_lshlrev_b32_e32 v90, 16, v47
	v_and_b32_e32 v91, 0xffff0000, v47
	s_waitcnt lgkmcnt(1)
	v_sub_f32_e32 v87, v87, v85
	v_sub_f32_e32 v86, v86, v85
	v_sub_f32_e32 v89, v89, v85
	v_sub_f32_e32 v88, v88, v85
	v_sub_f32_e32 v91, v91, v85
	v_sub_f32_e32 v90, v90, v85
	v_sub_f32_e32 v93, v93, v85
	v_sub_f32_e32 v92, v92, v85
	s_waitcnt lgkmcnt(0)
	v_pk_mul_f32 v[88:89], v[84:85], v[88:89] op_sel_hi:[0,1]
	v_pk_mul_f32 v[86:87], v[84:85], v[86:87] op_sel_hi:[0,1]
	v_pk_mul_f32 v[92:93], v[84:85], v[92:93] op_sel_hi:[0,1]
	v_pk_mul_f32 v[84:85], v[84:85], v[90:91] op_sel_hi:[0,1]
	v_pk_fma_f32 v[86:87], v[74:75], v[86:87], v[82:83]
	v_pk_fma_f32 v[88:89], v[72:73], v[88:89], v[80:81]
	v_pk_fma_f32 v[90:91], v[70:71], v[84:85], v[78:79]
	v_pk_fma_f32 v[92:93], v[68:69], v[92:93], v[76:77]
	v_cvt_pk_bf16_f32 v84, v88, v89
	v_cvt_pk_bf16_f32 v85, v86, v87
	v_cvt_pk_bf16_f32 v86, v92, v93
	v_cvt_pk_bf16_f32 v87, v90, v91
	ds_write_b128 v195, v[84:87] offset:51712
	ds_read_b32 v85, v211
	ds_read_b32 v84, v212
	v_lshlrev_b32_e32 v88, 16, v48
	v_and_b32_e32 v89, 0xffff0000, v48
	v_lshlrev_b32_e32 v86, 16, v49
	v_and_b32_e32 v87, 0xffff0000, v49
	v_lshlrev_b32_e32 v92, 16, v50
	v_and_b32_e32 v93, 0xffff0000, v50
	v_lshlrev_b32_e32 v90, 16, v51
	v_and_b32_e32 v91, 0xffff0000, v51
	s_waitcnt lgkmcnt(1)
	v_sub_f32_e32 v87, v87, v85
	v_sub_f32_e32 v86, v86, v85
	v_sub_f32_e32 v89, v89, v85
	v_sub_f32_e32 v88, v88, v85
	v_sub_f32_e32 v91, v91, v85
	v_sub_f32_e32 v90, v90, v85
	v_sub_f32_e32 v93, v93, v85
	v_sub_f32_e32 v92, v92, v85
	s_waitcnt lgkmcnt(0)
	v_pk_mul_f32 v[88:89], v[84:85], v[88:89] op_sel_hi:[0,1]
	v_pk_mul_f32 v[86:87], v[84:85], v[86:87] op_sel_hi:[0,1]
	v_pk_mul_f32 v[92:93], v[84:85], v[92:93] op_sel_hi:[0,1]
	v_pk_mul_f32 v[84:85], v[84:85], v[90:91] op_sel_hi:[0,1]
	v_pk_fma_f32 v[86:87], v[74:75], v[86:87], v[82:83]
	v_pk_fma_f32 v[88:89], v[72:73], v[88:89], v[80:81]
	v_pk_fma_f32 v[90:91], v[70:71], v[84:85], v[78:79]
	v_pk_fma_f32 v[92:93], v[68:69], v[92:93], v[76:77]
	v_cvt_pk_bf16_f32 v84, v88, v89
	v_cvt_pk_bf16_f32 v85, v86, v87
	v_cvt_pk_bf16_f32 v86, v92, v93
	v_cvt_pk_bf16_f32 v87, v90, v91
	ds_write_b128 v195, v[84:87] offset:60160
	ds_read_b32 v85, v213
	ds_read_b32 v84, v214
	v_lshlrev_b32_e32 v88, 16, v52
	v_and_b32_e32 v89, 0xffff0000, v52
	v_lshlrev_b32_e32 v86, 16, v53
	v_and_b32_e32 v87, 0xffff0000, v53
	v_lshlrev_b32_e32 v92, 16, v54
	v_and_b32_e32 v93, 0xffff0000, v54
	v_lshlrev_b32_e32 v90, 16, v55
	v_and_b32_e32 v91, 0xffff0000, v55
	s_waitcnt lgkmcnt(1)
	v_sub_f32_e32 v87, v87, v85
	v_sub_f32_e32 v86, v86, v85
	v_sub_f32_e32 v89, v89, v85
	v_sub_f32_e32 v88, v88, v85
	v_sub_f32_e32 v91, v91, v85
	v_sub_f32_e32 v90, v90, v85
	v_sub_f32_e32 v93, v93, v85
	v_sub_f32_e32 v92, v92, v85
	s_waitcnt lgkmcnt(0)
	v_pk_mul_f32 v[88:89], v[84:85], v[88:89] op_sel_hi:[0,1]
	v_pk_mul_f32 v[86:87], v[84:85], v[86:87] op_sel_hi:[0,1]
	v_pk_mul_f32 v[92:93], v[84:85], v[92:93] op_sel_hi:[0,1]
	v_pk_mul_f32 v[84:85], v[84:85], v[90:91] op_sel_hi:[0,1]
	v_pk_fma_f32 v[86:87], v[74:75], v[86:87], v[82:83]
	v_pk_fma_f32 v[88:89], v[72:73], v[88:89], v[80:81]
	v_pk_fma_f32 v[90:91], v[70:71], v[84:85], v[78:79]
	v_pk_fma_f32 v[92:93], v[68:69], v[92:93], v[76:77]
	v_cvt_pk_bf16_f32 v84, v88, v89
	v_cvt_pk_bf16_f32 v85, v86, v87
	v_cvt_pk_bf16_f32 v86, v92, v93
	v_cvt_pk_bf16_f32 v87, v90, v91
	ds_write_b128 v246, v[84:87] offset:34816
	ds_read_b32 v85, v215
	ds_read_b32 v84, v224
	v_lshlrev_b32_e32 v88, 16, v56
	v_and_b32_e32 v89, 0xffff0000, v56
	v_lshlrev_b32_e32 v86, 16, v57
	v_and_b32_e32 v87, 0xffff0000, v57
	v_lshlrev_b32_e32 v92, 16, v58
	v_and_b32_e32 v93, 0xffff0000, v58
	v_lshlrev_b32_e32 v90, 16, v59
	v_and_b32_e32 v91, 0xffff0000, v59
	s_waitcnt lgkmcnt(1)
	v_sub_f32_e32 v87, v87, v85
	v_sub_f32_e32 v86, v86, v85
	v_sub_f32_e32 v89, v89, v85
	v_sub_f32_e32 v88, v88, v85
	v_sub_f32_e32 v91, v91, v85
	v_sub_f32_e32 v90, v90, v85
	v_sub_f32_e32 v93, v93, v85
	v_sub_f32_e32 v92, v92, v85
	s_waitcnt lgkmcnt(0)
	v_pk_mul_f32 v[88:89], v[84:85], v[88:89] op_sel_hi:[0,1]
	v_pk_mul_f32 v[86:87], v[84:85], v[86:87] op_sel_hi:[0,1]
	v_pk_mul_f32 v[92:93], v[84:85], v[92:93] op_sel_hi:[0,1]
	v_pk_mul_f32 v[84:85], v[84:85], v[90:91] op_sel_hi:[0,1]
	v_pk_fma_f32 v[86:87], v[74:75], v[86:87], v[82:83]
	v_pk_fma_f32 v[88:89], v[72:73], v[88:89], v[80:81]
	v_pk_fma_f32 v[90:91], v[70:71], v[84:85], v[78:79]
	v_pk_fma_f32 v[92:93], v[68:69], v[92:93], v[76:77]
	v_cvt_pk_bf16_f32 v84, v88, v89
	v_cvt_pk_bf16_f32 v85, v86, v87
	v_cvt_pk_bf16_f32 v86, v92, v93
	v_cvt_pk_bf16_f32 v87, v90, v91
	ds_write_b128 v246, v[84:87] offset:43264
	ds_read_b32 v85, v225
	ds_read_b32 v84, v226
	v_lshlrev_b32_e32 v88, 16, v60
	v_and_b32_e32 v89, 0xffff0000, v60
	v_lshlrev_b32_e32 v86, 16, v61
	v_and_b32_e32 v87, 0xffff0000, v61
	v_lshlrev_b32_e32 v92, 16, v62
	v_and_b32_e32 v93, 0xffff0000, v62
	v_lshlrev_b32_e32 v90, 16, v63
	v_and_b32_e32 v91, 0xffff0000, v63
	s_waitcnt lgkmcnt(1)
	v_sub_f32_e32 v87, v87, v85
	v_sub_f32_e32 v86, v86, v85
	v_sub_f32_e32 v89, v89, v85
	v_sub_f32_e32 v88, v88, v85
	v_sub_f32_e32 v91, v91, v85
	v_sub_f32_e32 v90, v90, v85
	v_sub_f32_e32 v93, v93, v85
	v_sub_f32_e32 v92, v92, v85
	s_waitcnt lgkmcnt(0)
	v_pk_mul_f32 v[88:89], v[84:85], v[88:89] op_sel_hi:[0,1]
	v_pk_mul_f32 v[86:87], v[84:85], v[86:87] op_sel_hi:[0,1]
	v_pk_mul_f32 v[92:93], v[84:85], v[92:93] op_sel_hi:[0,1]
	v_pk_mul_f32 v[84:85], v[84:85], v[90:91] op_sel_hi:[0,1]
	v_pk_fma_f32 v[86:87], v[74:75], v[86:87], v[82:83]
	v_pk_fma_f32 v[88:89], v[72:73], v[88:89], v[80:81]
	v_pk_fma_f32 v[90:91], v[70:71], v[84:85], v[78:79]
	v_pk_fma_f32 v[92:93], v[68:69], v[92:93], v[76:77]
	v_cvt_pk_bf16_f32 v84, v88, v89
	v_cvt_pk_bf16_f32 v85, v86, v87
	v_cvt_pk_bf16_f32 v86, v92, v93
	v_cvt_pk_bf16_f32 v87, v90, v91
	ds_write_b128 v246, v[84:87] offset:51712
	ds_read_b32 v85, v227
	ds_read_b32 v84, v228
	v_lshlrev_b32_e32 v88, 16, v64
	v_and_b32_e32 v89, 0xffff0000, v64
	v_lshlrev_b32_e32 v86, 16, v65
	v_and_b32_e32 v87, 0xffff0000, v65
	v_lshlrev_b32_e32 v92, 16, v66
	v_and_b32_e32 v93, 0xffff0000, v66
	v_lshlrev_b32_e32 v90, 16, v67
	v_and_b32_e32 v91, 0xffff0000, v67
	s_waitcnt lgkmcnt(1)
	v_sub_f32_e32 v87, v87, v85
	v_sub_f32_e32 v86, v86, v85
	v_sub_f32_e32 v89, v89, v85
	v_sub_f32_e32 v88, v88, v85
	v_sub_f32_e32 v91, v91, v85
	v_sub_f32_e32 v90, v90, v85
	v_sub_f32_e32 v93, v93, v85
	v_sub_f32_e32 v92, v92, v85
	s_waitcnt lgkmcnt(0)
	v_pk_mul_f32 v[88:89], v[84:85], v[88:89] op_sel_hi:[0,1]
	v_pk_mul_f32 v[86:87], v[84:85], v[86:87] op_sel_hi:[0,1]
	v_pk_mul_f32 v[92:93], v[84:85], v[92:93] op_sel_hi:[0,1]
	v_pk_mul_f32 v[84:85], v[84:85], v[90:91] op_sel_hi:[0,1]
	v_pk_fma_f32 v[86:87], v[74:75], v[86:87], v[82:83]
	v_pk_fma_f32 v[88:89], v[72:73], v[88:89], v[80:81]
	v_pk_fma_f32 v[90:91], v[70:71], v[84:85], v[78:79]
	v_pk_fma_f32 v[92:93], v[68:69], v[92:93], v[76:77]
	v_cvt_pk_bf16_f32 v84, v88, v89
	v_cvt_pk_bf16_f32 v85, v86, v87
	v_cvt_pk_bf16_f32 v86, v92, v93
	v_cvt_pk_bf16_f32 v87, v90, v91
	s_add_u32 s78, s5, s76
	ds_write_b128 v246, v[84:87] offset:60160
	v_mov_b32_e32 v84, v201
	v_mov_b32_e32 v85, v2
	s_addc_u32 s79, s81, s77
	s_waitcnt lgkmcnt(0)
	s_barrier
	s_mov_b32 s3, 0x9900000
	v_lshl_add_u64 v[86:87], v[84:85], 1, s[78:79]
	v_add_co_u32_e32 v86, vcc, s3, v86
	v_add_u32_e32 v190, v229, v203
	s_nop 0
	v_addc_co_u32_e32 v87, vcc, 0, v87, vcc
	global_load_dwordx4 v[112:115], v[86:87], off
	v_add_u32_e32 v86, 0x8000, v84
	v_mov_b32_e32 v87, v2
	v_lshl_add_u64 v[86:87], v[86:87], 1, s[78:79]
	v_add_co_u32_e32 v86, vcc, s3, v86
	s_cmpk_lg_i32 s76, 0xe00
	s_nop 0
	v_addc_co_u32_e32 v87, vcc, 0, v87, vcc
	global_load_dwordx4 v[108:111], v[86:87], off
	v_add_u32_e32 v86, 0x10000, v84
	v_mov_b32_e32 v87, v2
	v_lshl_add_u64 v[86:87], v[86:87], 1, s[78:79]
	v_add_co_u32_e32 v86, vcc, s3, v86
	s_cselect_b64 s[98:99], -1, 0
	s_nop 0
	v_addc_co_u32_e32 v87, vcc, 0, v87, vcc
	global_load_dwordx4 v[104:107], v[86:87], off
	v_add_u32_e32 v86, 0x18000, v84
	v_mov_b32_e32 v87, v2
	v_lshl_add_u64 v[86:87], v[86:87], 1, s[78:79]
	v_add_co_u32_e32 v86, vcc, s3, v86
	s_cmpk_eq_i32 s76, 0xe00
	s_nop 0
	v_addc_co_u32_e32 v87, vcc, 0, v87, vcc
	global_load_dwordx4 v[100:103], v[86:87], off
	v_add_u32_e32 v86, 0x20000, v84
	v_mov_b32_e32 v87, v2
	v_lshl_add_u64 v[86:87], v[86:87], 1, s[78:79]
	v_add_co_u32_e32 v86, vcc, s3, v86
	s_nop 1
	v_addc_co_u32_e32 v87, vcc, 0, v87, vcc
	global_load_dwordx4 v[96:99], v[86:87], off
	v_add_u32_e32 v86, 0x28000, v84
	v_mov_b32_e32 v87, v2
	v_lshl_add_u64 v[86:87], v[86:87], 1, s[78:79]
	v_add_co_u32_e32 v86, vcc, s3, v86
	s_nop 1
	v_addc_co_u32_e32 v87, vcc, 0, v87, vcc
	global_load_dwordx4 v[92:95], v[86:87], off
	v_add_u32_e32 v86, 0x30000, v84
	v_mov_b32_e32 v87, v2
	v_lshl_add_u64 v[86:87], v[86:87], 1, s[78:79]
	v_add_co_u32_e32 v86, vcc, s3, v86
	v_add_u32_e32 v84, 0x38000, v84
	s_nop 0
	v_addc_co_u32_e32 v87, vcc, 0, v87, vcc
	v_lshl_add_u64 v[84:85], v[84:85], 1, s[78:79]
	v_add_co_u32_e32 v84, vcc, s3, v84
	global_load_dwordx4 v[88:91], v[86:87], off
	s_nop 0
	v_addc_co_u32_e32 v85, vcc, 0, v85, vcc
	global_load_dwordx4 v[84:87], v[84:85], off
	ds_read_b64_tr_b16 v[134:135], v190 offset:36928
	ds_read_b64_tr_b16 v[132:133], v190 offset:34816
	ds_read_b64_tr_b16 v[136:137], v190 offset:34848
	ds_read_b64_tr_b16 v[138:139], v190 offset:36960
	ds_read_b128 v[116:119], v242
	s_waitcnt lgkmcnt(0)
	v_mfma_f32_16x16x32_bf16 v[128:131], v[132:135], v[116:119], 0
	ds_read_b128 v[140:143], v242 offset:8704
	v_mfma_f32_16x16x32_bf16 v[120:123], v[136:139], v[116:119], 0
	ds_read_b128 v[116:119], v242 offset:4352
	s_waitcnt lgkmcnt(1)
	v_mfma_f32_16x16x32_bf16 v[144:147], v[132:135], v[140:143], 0
	v_mfma_f32_16x16x32_bf16 v[148:151], v[136:139], v[140:143], 0
	ds_read_b128 v[140:143], v242 offset:13056
	s_waitcnt lgkmcnt(0)
	v_mfma_f32_16x16x32_bf16 v[152:155], v[132:135], v[140:143], 0
	v_mfma_f32_16x16x32_bf16 v[156:159], v[136:139], v[140:143], 0
	ds_read_b128 v[140:143], v242 offset:17408
	s_waitcnt lgkmcnt(0)
	v_mfma_f32_16x16x32_bf16 v[160:163], v[132:135], v[140:143], 0
	v_mfma_f32_16x16x32_bf16 v[164:167], v[136:139], v[140:143], 0
	ds_read_b128 v[140:143], v242 offset:21760
	s_waitcnt lgkmcnt(0)
	v_mfma_f32_16x16x32_bf16 v[168:171], v[132:135], v[140:143], 0
	v_mfma_f32_16x16x32_bf16 v[172:175], v[136:139], v[140:143], 0
	ds_read_b128 v[140:143], v242 offset:26112
	s_waitcnt lgkmcnt(0)
	v_mfma_f32_16x16x32_bf16 v[176:179], v[132:135], v[140:143], 0
	v_mfma_f32_16x16x32_bf16 v[180:183], v[136:139], v[140:143], 0
	ds_read_b128 v[140:143], v242 offset:30464
	v_mfma_f32_16x16x32_bf16 v[124:127], v[132:135], v[116:119], 0
	s_waitcnt lgkmcnt(0)
	v_mfma_f32_16x16x32_bf16 v[184:187], v[132:135], v[140:143], 0
	ds_read_b64_tr_b16 v[216:217], v190 offset:51712
	ds_read_b64_tr_b16 v[218:219], v190 offset:53824
	ds_read_b64_tr_b16 v[188:189], v190 offset:51744
	ds_read_b64_tr_b16 v[190:191], v190 offset:53856
	ds_read_b128 v[132:135], v242 offset:8768
	v_mfma_f32_16x16x32_bf16 v[116:119], v[136:139], v[116:119], 0
	v_mfma_f32_16x16x32_bf16 v[248:251], v[136:139], v[140:143], 0
	ds_read_b128 v[136:139], v242 offset:13120
	s_waitcnt lgkmcnt(1)
	v_mfma_f32_16x16x32_bf16 v[140:143], v[216:219], v[132:135], v[144:147]
	v_mfma_f32_16x16x32_bf16 v[132:135], v[188:191], v[132:135], v[148:151]
	s_nop 2
	ds_read_b128 v[148:151], v242 offset:17472
	s_waitcnt lgkmcnt(1)
	v_mfma_f32_16x16x32_bf16 v[144:147], v[216:219], v[136:139], v[152:155]
	s_waitcnt lgkmcnt(0)
	v_mfma_f32_16x16x32_bf16 v[152:155], v[216:219], v[148:151], v[160:163]
	s_nop 2
	ds_read_b128 v[160:163], v242 offset:21824
	v_mfma_f32_16x16x32_bf16 v[136:139], v[188:191], v[136:139], v[156:159]
	s_waitcnt lgkmcnt(0)
	v_mfma_f32_16x16x32_bf16 v[156:159], v[216:219], v[160:163], v[168:171]
	s_nop 2
	ds_read_b128 v[168:171], v242 offset:26176
	v_mfma_f32_16x16x32_bf16 v[148:151], v[188:191], v[148:151], v[164:167]
	s_waitcnt lgkmcnt(0)
	v_mfma_f32_16x16x32_bf16 v[164:167], v[216:219], v[168:171], v[176:179]
	s_nop 2
	ds_read_b128 v[176:179], v242 offset:30528
	v_mfma_f32_16x16x32_bf16 v[160:163], v[188:191], v[160:163], v[172:175]
	v_mfma_f32_16x16x32_bf16 v[168:171], v[188:191], v[168:171], v[180:183]
	s_waitcnt lgkmcnt(0)
	v_mfma_f32_16x16x32_bf16 v[172:175], v[216:219], v[176:179], v[184:187]
	v_mfma_f32_16x16x32_bf16 v[176:179], v[188:191], v[176:179], v[248:251]
	ds_read_b64_tr_b16 v[182:183], v243 offset:35904
	ds_read_b64_tr_b16 v[180:181], v243 offset:33792
	ds_read_b64_tr_b16 v[184:185], v243 offset:33824
	ds_read_b64_tr_b16 v[186:187], v243 offset:35936
	ds_read_b128 v[188:191], v242 offset:17536
	s_waitcnt lgkmcnt(0)
	v_mfma_f32_16x16x32_bf16 v[152:155], v[180:183], v[188:191], v[152:155]
	v_mfma_f32_16x16x32_bf16 v[148:151], v[184:187], v[188:191], v[148:151]
	ds_read_b128 v[188:191], v242 offset:21888
	s_waitcnt lgkmcnt(0)
	v_mfma_f32_16x16x32_bf16 v[156:159], v[180:183], v[188:191], v[156:159]
	v_mfma_f32_16x16x32_bf16 v[160:163], v[184:187], v[188:191], v[160:163]
	ds_read_b128 v[188:191], v242 offset:26240
	s_waitcnt lgkmcnt(0)
	v_mfma_f32_16x16x32_bf16 v[164:167], v[180:183], v[188:191], v[164:167]
	v_mfma_f32_16x16x32_bf16 v[188:191], v[184:187], v[188:191], v[168:171]
	s_nop 2
	ds_read_b128 v[168:171], v242 offset:30592
	s_waitcnt lgkmcnt(0)
	v_mfma_f32_16x16x32_bf16 v[172:175], v[180:183], v[168:171], v[172:175]
	v_mfma_f32_16x16x32_bf16 v[180:183], v[184:187], v[168:171], v[176:179]
	s_nop 2
	ds_read_b64_tr_b16 v[176:177], v243 offset:50688
	ds_read_b64_tr_b16 v[178:179], v243 offset:52800
	ds_read_b64_tr_b16 v[184:185], v243 offset:50720
	ds_read_b64_tr_b16 v[186:187], v243 offset:52832
	ds_read_b128 v[216:219], v242 offset:26304
	s_waitcnt lgkmcnt(0)
	v_mfma_f32_16x16x32_bf16 v[168:171], v[176:179], v[216:219], v[164:167]
	v_mfma_f32_16x16x32_bf16 v[164:167], v[184:187], v[216:219], v[188:191]
	s_nop 2
	ds_read_b128 v[188:191], v242 offset:30656
	s_waitcnt lgkmcnt(0)
	v_mfma_f32_16x16x32_bf16 v[176:179], v[176:179], v[188:191], v[172:175]
	v_mfma_f32_16x16x32_bf16 v[172:175], v[184:187], v[188:191], v[180:183]
	s_mov_b32 s32, 0
	s_cbranch_scc1 .LBB0_538
	s_mov_b32 s32, 1
	s_add_u32 s78, s5, s76
	v_mov_b32_e32 v60, v201
	v_mov_b32_e32 v61, v2
	s_addc_u32 s79, s81, s77
	v_mov_b32_e32 v35, v2
	v_lshl_add_u64 v[32:33], v[60:61], 1, s[78:79]
	v_add_co_u32_e32 v32, vcc, 0x11900000, v32
	v_add_u32_e32 v34, 0x8000, v60
	s_nop 0
	v_addc_co_u32_e32 v33, vcc, 0, v33, vcc
	v_lshl_add_u64 v[34:35], v[34:35], 1, s[78:79]
	v_add_co_u32_e32 v40, vcc, 0x11900000, v34
	v_add_u32_e32 v44, 0x10000, v60
	v_mov_b32_e32 v45, v2
	v_addc_co_u32_e32 v41, vcc, 0, v35, vcc
	v_lshl_add_u64 v[44:45], v[44:45], 1, s[78:79]
	v_add_co_u32_e32 v44, vcc, 0x11900000, v44
	v_add_u32_e32 v46, 0x18000, v60
	v_mov_b32_e32 v47, v2
	v_addc_co_u32_e32 v45, vcc, 0, v45, vcc
	v_lshl_add_u64 v[46:47], v[46:47], 1, s[78:79]
	v_add_co_u32_e32 v48, vcc, 0x11900000, v46
	v_add_u32_e32 v52, 0x20000, v60
	v_mov_b32_e32 v53, v2
	v_addc_co_u32_e32 v49, vcc, 0, v47, vcc
	v_lshl_add_u64 v[52:53], v[52:53], 1, s[78:79]
	v_add_co_u32_e32 v52, vcc, 0x11900000, v52
	v_add_u32_e32 v54, 0x28000, v60
	v_mov_b32_e32 v55, v2
	v_addc_co_u32_e32 v53, vcc, 0, v53, vcc
	v_lshl_add_u64 v[54:55], v[54:55], 1, s[78:79]
	v_add_co_u32_e32 v56, vcc, 0x11900000, v54
	v_add_u32_e32 v62, 0x30000, v60
	v_mov_b32_e32 v63, v2
	v_addc_co_u32_e32 v57, vcc, 0, v55, vcc
	v_lshl_add_u64 v[62:63], v[62:63], 1, s[78:79]
	v_add_co_u32_e32 v62, vcc, 0x11900000, v62
	v_add_u32_e32 v60, 0x38000, v60
	s_nop 0
	v_addc_co_u32_e32 v63, vcc, 0, v63, vcc
	v_lshl_add_u64 v[60:61], v[60:61], 1, s[78:79]
	v_add_co_u32_e32 v64, vcc, 0x11900000, v60
	v_lshl_add_u64 v[72:73], s[0:1], 0, v[192:193]
	s_nop 0
	v_addc_co_u32_e32 v65, vcc, 0, v61, vcc
	v_lshl_add_u64 v[80:81], s[90:91], 0, v[192:193]
	global_load_dwordx4 v[32:35], v[32:33], off offset:512
	s_nop 0
	global_load_dwordx4 v[40:43], v[40:41], off offset:512
	s_nop 0
	global_load_dwordx4 v[44:47], v[44:45], off offset:512
	s_nop 0
	global_load_dwordx4 v[48:51], v[48:49], off offset:512
	s_nop 0
	global_load_dwordx4 v[52:55], v[52:53], off offset:512
	s_nop 0
	global_load_dwordx4 v[56:59], v[56:57], off offset:512
	s_nop 0
	global_load_dwordx4 v[60:63], v[62:63], off offset:512
	s_nop 0
	global_load_dwordx4 v[64:67], v[64:65], off offset:512
	s_nop 0
	global_load_dwordx4 v[68:71], v[72:73], off offset:1040
	s_nop 0
	global_load_dwordx4 v[72:75], v[72:73], off offset:1024
	s_nop 0
	global_load_dwordx4 v[76:79], v[80:81], off offset:1040
	s_nop 0
	global_load_dwordx4 v[80:83], v[80:81], off offset:1024
.LBB0_538:
	s_barrier
	s_nop 0
	ds_read_b32 v180, v230
	s_add_u32 s82, s5, s76
	s_addc_u32 s83, s81, s77
	s_waitcnt lgkmcnt(0)
	v_pk_add_f32 v[130:131], v[130:131], v[180:181] op_sel_hi:[1,0]
	v_pk_add_f32 v[128:129], v[128:129], v[180:181] op_sel_hi:[1,0]
	v_pk_add_f32 v[122:123], v[122:123], v[180:181] op_sel_hi:[1,0]
	v_pk_add_f32 v[120:121], v[120:121], v[180:181] op_sel_hi:[1,0]
	v_cvt_pk_bf16_f32 v128, v128, v129
	v_cvt_pk_bf16_f32 v129, v130, v131
	v_cvt_pk_bf16_f32 v120, v120, v121
	v_cvt_pk_bf16_f32 v121, v122, v123
	v_add_u32_e32 v122, 0x8800, v244
	ds_write2_b64 v122, v[128:129], v[120:121] offset1:4
	ds_read_b32 v120, v231
	s_waitcnt lgkmcnt(0)
	v_pk_add_f32 v[122:123], v[126:127], v[120:121] op_sel_hi:[1,0]
	v_pk_add_f32 v[124:125], v[124:125], v[120:121] op_sel_hi:[1,0]
	v_pk_add_f32 v[118:119], v[118:119], v[120:121] op_sel_hi:[1,0]
	v_pk_add_f32 v[116:117], v[116:117], v[120:121] op_sel_hi:[1,0]
	v_cvt_pk_bf16_f32 v124, v124, v125
	v_cvt_pk_bf16_f32 v125, v122, v123
	v_cvt_pk_bf16_f32 v116, v116, v117
	v_cvt_pk_bf16_f32 v117, v118, v119
	v_add_u32_e32 v118, 0xa800, v244
	ds_write2_b64 v118, v[124:125], v[116:117] offset0:32 offset1:36
	ds_read_b32 v116, v232
	s_cmp_lg_u32 s32, 0
	s_cbranch_scc1 .Lspw0_a
	s_waitcnt vmcnt(7)
	s_branch .Lspw0_j
.Lspw0_a:
	s_waitcnt vmcnt(19)
.Lspw0_j:
	v_lshlrev_b32_e32 v126, 16, v112
	v_and_b32_e32 v127, 0xffff0000, v112
	s_waitcnt lgkmcnt(0)
	v_pk_add_f32 v[118:119], v[142:143], v[116:117] op_sel_hi:[1,0]
	v_pk_add_f32 v[120:121], v[140:141], v[116:117] op_sel_hi:[1,0]
	s_nop 0
	v_cvt_pk_bf16_f32 v120, v120, v121
	v_cvt_pk_bf16_f32 v121, v118, v119
	v_pk_add_f32 v[118:119], v[134:135], v[116:117] op_sel_hi:[1,0]
	v_pk_add_f32 v[116:117], v[132:133], v[116:117] op_sel_hi:[1,0]
	s_nop 0
	v_cvt_pk_bf16_f32 v116, v116, v117
	v_cvt_pk_bf16_f32 v117, v118, v119
	v_add_u32_e32 v118, 0xc800, v244
	ds_write2_b64 v118, v[120:121], v[116:117] offset0:64 offset1:68
	ds_read_b32 v116, v233
	s_waitcnt lgkmcnt(0)
	v_pk_add_f32 v[118:119], v[146:147], v[116:117] op_sel_hi:[1,0]
	v_pk_add_f32 v[120:121], v[144:145], v[116:117] op_sel_hi:[1,0]
	s_nop 0
	v_cvt_pk_bf16_f32 v120, v120, v121
	v_cvt_pk_bf16_f32 v121, v118, v119
	v_pk_add_f32 v[118:119], v[138:139], v[116:117] op_sel_hi:[1,0]
	v_pk_add_f32 v[116:117], v[136:137], v[116:117] op_sel_hi:[1,0]
	s_nop 0
	v_cvt_pk_bf16_f32 v116, v116, v117
	v_cvt_pk_bf16_f32 v117, v118, v119
	v_add_u32_e32 v118, 0xe800, v244
	ds_write2_b64 v118, v[120:121], v[116:117] offset0:96 offset1:100
	ds_read_b32 v116, v234
	s_waitcnt lgkmcnt(0)
	v_pk_add_f32 v[118:119], v[154:155], v[116:117] op_sel_hi:[1,0]
	v_pk_add_f32 v[120:121], v[152:153], v[116:117] op_sel_hi:[1,0]
	s_nop 0
	v_cvt_pk_bf16_f32 v120, v120, v121
	v_cvt_pk_bf16_f32 v121, v118, v119
	v_pk_add_f32 v[118:119], v[150:151], v[116:117] op_sel_hi:[1,0]
	v_pk_add_f32 v[116:117], v[148:149], v[116:117] op_sel_hi:[1,0]
	s_nop 0
	v_cvt_pk_bf16_f32 v116, v116, v117
	v_cvt_pk_bf16_f32 v117, v118, v119
	v_add_u32_e32 v118, 0x8800, v245
	ds_write2_b64 v118, v[120:121], v[116:117] offset1:4
	ds_read_b32 v116, v235
	s_waitcnt lgkmcnt(0)
	v_pk_add_f32 v[118:119], v[158:159], v[116:117] op_sel_hi:[1,0]
	v_pk_add_f32 v[120:121], v[156:157], v[116:117] op_sel_hi:[1,0]
	s_nop 0
	v_cvt_pk_bf16_f32 v120, v120, v121
	v_cvt_pk_bf16_f32 v121, v118, v119
	v_pk_add_f32 v[118:119], v[162:163], v[116:117] op_sel_hi:[1,0]
	v_pk_add_f32 v[116:117], v[160:161], v[116:117] op_sel_hi:[1,0]
	s_nop 0
	v_cvt_pk_bf16_f32 v116, v116, v117
	v_cvt_pk_bf16_f32 v117, v118, v119
	v_add_u32_e32 v118, 0xa800, v245
	ds_write2_b64 v118, v[120:121], v[116:117] offset0:32 offset1:36
	ds_read_b32 v116, v236
	s_waitcnt lgkmcnt(0)
	v_pk_add_f32 v[118:119], v[170:171], v[116:117] op_sel_hi:[1,0]
	v_pk_add_f32 v[120:121], v[168:169], v[116:117] op_sel_hi:[1,0]
	s_nop 0
	v_cvt_pk_bf16_f32 v120, v120, v121
	v_cvt_pk_bf16_f32 v121, v118, v119
	v_pk_add_f32 v[118:119], v[166:167], v[116:117] op_sel_hi:[1,0]
	v_pk_add_f32 v[116:117], v[164:165], v[116:117] op_sel_hi:[1,0]
	s_nop 0
	v_cvt_pk_bf16_f32 v116, v116, v117
	v_cvt_pk_bf16_f32 v117, v118, v119
	v_add_u32_e32 v118, 0xc800, v245
	ds_write2_b64 v118, v[120:121], v[116:117] offset0:64 offset1:68
	ds_read_b32 v116, v237
	s_waitcnt lgkmcnt(0)
	v_pk_add_f32 v[118:119], v[178:179], v[116:117] op_sel_hi:[1,0]
	v_pk_add_f32 v[120:121], v[176:177], v[116:117] op_sel_hi:[1,0]
	s_nop 0
	v_cvt_pk_bf16_f32 v120, v120, v121
	v_cvt_pk_bf16_f32 v121, v118, v119
	v_pk_add_f32 v[118:119], v[174:175], v[116:117] op_sel_hi:[1,0]
	v_pk_add_f32 v[116:117], v[172:173], v[116:117] op_sel_hi:[1,0]
	s_nop 0
	v_cvt_pk_bf16_f32 v116, v116, v117
	v_cvt_pk_bf16_f32 v117, v118, v119
	v_add_u32_e32 v118, 0xe800, v245
	ds_write2_b64 v118, v[120:121], v[116:117] offset0:96 offset1:100
	v_mov_b32_e32 v116, v201
	s_waitcnt lgkmcnt(0)
	s_barrier
	ds_read_b128 v[118:121], v195 offset:34816
	ds_read_b128 v[122:125], v195 offset:43264
	v_mov_b32_e32 v117, v2
	s_waitcnt lgkmcnt(1)
	v_lshlrev_b32_e32 v128, 16, v118
	v_and_b32_e32 v129, 0xffff0000, v118
	v_pk_mul_f32 v[126:127], v[126:127], v[128:129]
	v_lshlrev_b32_e32 v118, 16, v119
	v_cvt_pk_bf16_f32 v112, v126, v127
	v_lshlrev_b32_e32 v126, 16, v113
	v_and_b32_e32 v127, 0xffff0000, v113
	v_and_b32_e32 v119, 0xffff0000, v119
	v_pk_mul_f32 v[118:119], v[126:127], v[118:119]
	v_lshlrev_b32_e32 v126, 16, v120
	v_cvt_pk_bf16_f32 v113, v118, v119
	v_lshlrev_b32_e32 v118, 16, v114
	v_and_b32_e32 v119, 0xffff0000, v114
	v_and_b32_e32 v127, 0xffff0000, v120
	v_pk_mul_f32 v[118:119], v[118:119], v[126:127]
	v_lshlrev_b32_e32 v120, 16, v121
	v_cvt_pk_bf16_f32 v114, v118, v119
	v_lshlrev_b32_e32 v118, 16, v115
	v_and_b32_e32 v119, 0xffff0000, v115
	v_and_b32_e32 v121, 0xffff0000, v121
	v_pk_mul_f32 v[118:119], v[118:119], v[120:121]
	s_nop 0
	v_cvt_pk_bf16_f32 v115, v118, v119
	v_lshl_add_u64 v[118:119], v[116:117], 1, s[82:83]
	v_add_co_u32_e32 v118, vcc, s3, v118
	s_nop 1
	v_addc_co_u32_e32 v119, vcc, 0, v119, vcc
	global_store_dwordx4 v[118:119], v[112:115], off
	s_cmp_lg_u32 s32, 0
	s_cbranch_scc1 .Lspw1_a
	s_waitcnt vmcnt(7)
	s_branch .Lspw1_j

.Lspw1_j:
	s_nop 0
	v_lshlrev_b32_e32 v112, 16, v108
	v_and_b32_e32 v113, 0xffff0000, v108
	s_waitcnt lgkmcnt(0)
	v_lshlrev_b32_e32 v114, 16, v122
	v_and_b32_e32 v115, 0xffff0000, v122
	v_pk_mul_f32 v[112:113], v[112:113], v[114:115]
	v_lshlrev_b32_e32 v114, 16, v123
	v_cvt_pk_bf16_f32 v108, v112, v113
	v_lshlrev_b32_e32 v112, 16, v109
	v_and_b32_e32 v113, 0xffff0000, v109
	v_and_b32_e32 v115, 0xffff0000, v123
	v_pk_mul_f32 v[112:113], v[112:113], v[114:115]
	v_lshlrev_b32_e32 v114, 16, v124
	v_cvt_pk_bf16_f32 v109, v112, v113
	v_lshlrev_b32_e32 v112, 16, v110
	v_and_b32_e32 v113, 0xffff0000, v110
	v_and_b32_e32 v115, 0xffff0000, v124
	v_pk_mul_f32 v[112:113], v[112:113], v[114:115]
	v_lshlrev_b32_e32 v114, 16, v125
	v_cvt_pk_bf16_f32 v110, v112, v113
	v_lshlrev_b32_e32 v112, 16, v111
	v_and_b32_e32 v113, 0xffff0000, v111
	v_and_b32_e32 v115, 0xffff0000, v125
	v_pk_mul_f32 v[112:113], v[112:113], v[114:115]
	s_nop 0
	v_cvt_pk_bf16_f32 v111, v112, v113
	v_add_u32_e32 v112, 0x8000, v116
	v_mov_b32_e32 v113, v2
	v_lshl_add_u64 v[112:113], v[112:113], 1, s[82:83]
	v_add_co_u32_e32 v118, vcc, s3, v112
	s_nop 1
	v_addc_co_u32_e32 v119, vcc, 0, v113, vcc
	ds_read_b128 v[112:115], v195 offset:51712
	global_store_dwordx4 v[118:119], v[108:111], off
	s_cmp_lg_u32 s32, 0
	s_cbranch_scc1 .Lspw2_a
	s_waitcnt vmcnt(7)
	s_branch .Lspw2_j

.Lspw2_j:
	v_lshlrev_b32_e32 v118, 16, v104
	v_and_b32_e32 v119, 0xffff0000, v104
	ds_read_b128 v[108:111], v195 offset:60160
	s_waitcnt lgkmcnt(1)
	v_lshlrev_b32_e32 v120, 16, v112
	v_and_b32_e32 v121, 0xffff0000, v112
	v_pk_mul_f32 v[118:119], v[118:119], v[120:121]
	v_lshlrev_b32_e32 v112, 16, v113
	v_cvt_pk_bf16_f32 v104, v118, v119
	v_lshlrev_b32_e32 v118, 16, v105
	v_and_b32_e32 v119, 0xffff0000, v105
	v_and_b32_e32 v113, 0xffff0000, v113
	v_pk_mul_f32 v[112:113], v[118:119], v[112:113]
	v_lshlrev_b32_e32 v118, 16, v114
	v_cvt_pk_bf16_f32 v105, v112, v113
	v_lshlrev_b32_e32 v112, 16, v106
	v_and_b32_e32 v113, 0xffff0000, v106
	v_and_b32_e32 v119, 0xffff0000, v114
	v_pk_mul_f32 v[112:113], v[112:113], v[118:119]
	v_lshlrev_b32_e32 v114, 16, v115
	v_cvt_pk_bf16_f32 v106, v112, v113
	v_lshlrev_b32_e32 v112, 16, v107
	v_and_b32_e32 v113, 0xffff0000, v107
	v_and_b32_e32 v115, 0xffff0000, v115
	v_pk_mul_f32 v[112:113], v[112:113], v[114:115]
	s_nop 0
	v_cvt_pk_bf16_f32 v107, v112, v113
	v_add_u32_e32 v112, 0x10000, v116
	v_mov_b32_e32 v113, v2
	v_lshl_add_u64 v[112:113], v[112:113], 1, s[82:83]
	v_add_co_u32_e32 v112, vcc, s3, v112
	s_nop 1
	v_addc_co_u32_e32 v113, vcc, 0, v113, vcc
	global_store_dwordx4 v[112:113], v[104:107], off
	s_cmp_lg_u32 s32, 0
	s_cbranch_scc1 .Lspw3_a
	s_waitcnt vmcnt(7)
	s_branch .Lspw3_j

.Lspw3_j:
	s_nop 0
	v_lshlrev_b32_e32 v104, 16, v100
	v_and_b32_e32 v105, 0xffff0000, v100
	s_waitcnt lgkmcnt(0)
	v_lshlrev_b32_e32 v106, 16, v108
	v_and_b32_e32 v107, 0xffff0000, v108
	v_pk_mul_f32 v[104:105], v[104:105], v[106:107]
	v_lshlrev_b32_e32 v106, 16, v109
	v_cvt_pk_bf16_f32 v100, v104, v105
	v_lshlrev_b32_e32 v104, 16, v101
	v_and_b32_e32 v105, 0xffff0000, v101
	v_and_b32_e32 v107, 0xffff0000, v109
	v_pk_mul_f32 v[104:105], v[104:105], v[106:107]
	v_lshlrev_b32_e32 v106, 16, v110
	v_cvt_pk_bf16_f32 v101, v104, v105
	v_lshlrev_b32_e32 v104, 16, v102
	v_and_b32_e32 v105, 0xffff0000, v102
	v_and_b32_e32 v107, 0xffff0000, v110
	v_pk_mul_f32 v[104:105], v[104:105], v[106:107]
	v_lshlrev_b32_e32 v106, 16, v111
	v_cvt_pk_bf16_f32 v102, v104, v105
	v_lshlrev_b32_e32 v104, 16, v103
	v_and_b32_e32 v105, 0xffff0000, v103
	v_and_b32_e32 v107, 0xffff0000, v111
	v_pk_mul_f32 v[104:105], v[104:105], v[106:107]
	s_nop 0
	v_cvt_pk_bf16_f32 v103, v104, v105
	v_add_u32_e32 v104, 0x18000, v116
	v_mov_b32_e32 v105, v2
	v_lshl_add_u64 v[104:105], v[104:105], 1, s[82:83]
	v_add_co_u32_e32 v108, vcc, s3, v104
	s_nop 1
	v_addc_co_u32_e32 v109, vcc, 0, v105, vcc
	ds_read_b128 v[104:107], v246 offset:34816
	global_store_dwordx4 v[108:109], v[100:103], off
	s_cmp_lg_u32 s32, 0
	s_cbranch_scc1 .Lspw4_a
	s_waitcnt vmcnt(7)
	s_branch .Lspw4_j

.Lspw4_j:
	v_lshlrev_b32_e32 v108, 16, v96
	v_and_b32_e32 v109, 0xffff0000, v96
	ds_read_b128 v[100:103], v246 offset:43264
	s_waitcnt lgkmcnt(1)
	v_lshlrev_b32_e32 v110, 16, v104
	v_and_b32_e32 v111, 0xffff0000, v104
	v_pk_mul_f32 v[108:109], v[108:109], v[110:111]
	v_lshlrev_b32_e32 v104, 16, v105
	v_cvt_pk_bf16_f32 v96, v108, v109
	v_lshlrev_b32_e32 v108, 16, v97
	v_and_b32_e32 v109, 0xffff0000, v97
	v_and_b32_e32 v105, 0xffff0000, v105
	v_pk_mul_f32 v[104:105], v[108:109], v[104:105]
	v_lshlrev_b32_e32 v108, 16, v106
	v_cvt_pk_bf16_f32 v97, v104, v105
	v_lshlrev_b32_e32 v104, 16, v98
	v_and_b32_e32 v105, 0xffff0000, v98
	v_and_b32_e32 v109, 0xffff0000, v106
	v_pk_mul_f32 v[104:105], v[104:105], v[108:109]
	v_lshlrev_b32_e32 v106, 16, v107
	v_cvt_pk_bf16_f32 v98, v104, v105
	v_lshlrev_b32_e32 v104, 16, v99
	v_and_b32_e32 v105, 0xffff0000, v99
	v_and_b32_e32 v107, 0xffff0000, v107
	v_pk_mul_f32 v[104:105], v[104:105], v[106:107]
	s_nop 0
	v_cvt_pk_bf16_f32 v99, v104, v105
	v_add_u32_e32 v104, 0x20000, v116
	v_mov_b32_e32 v105, v2
	v_lshl_add_u64 v[104:105], v[104:105], 1, s[82:83]
	v_add_co_u32_e32 v104, vcc, s3, v104
	s_nop 1
	v_addc_co_u32_e32 v105, vcc, 0, v105, vcc
	global_store_dwordx4 v[104:105], v[96:99], off
	s_cmp_lg_u32 s32, 0
	s_cbranch_scc1 .Lspw5_a
	s_waitcnt vmcnt(7)
	s_branch .Lspw5_j

.Lspw5_j:
	s_nop 0
	v_lshlrev_b32_e32 v96, 16, v92
	v_and_b32_e32 v97, 0xffff0000, v92
	s_waitcnt lgkmcnt(0)
	v_lshlrev_b32_e32 v98, 16, v100
	v_and_b32_e32 v99, 0xffff0000, v100
	v_pk_mul_f32 v[96:97], v[96:97], v[98:99]
	v_lshlrev_b32_e32 v98, 16, v101
	v_cvt_pk_bf16_f32 v92, v96, v97
	v_lshlrev_b32_e32 v96, 16, v93
	v_and_b32_e32 v97, 0xffff0000, v93
	v_and_b32_e32 v99, 0xffff0000, v101
	v_pk_mul_f32 v[96:97], v[96:97], v[98:99]
	v_lshlrev_b32_e32 v98, 16, v102
	v_cvt_pk_bf16_f32 v93, v96, v97
	v_lshlrev_b32_e32 v96, 16, v94
	v_and_b32_e32 v97, 0xffff0000, v94
	v_and_b32_e32 v99, 0xffff0000, v102
	v_pk_mul_f32 v[96:97], v[96:97], v[98:99]
	v_lshlrev_b32_e32 v98, 16, v103
	v_cvt_pk_bf16_f32 v94, v96, v97
	v_lshlrev_b32_e32 v96, 16, v95
	v_and_b32_e32 v97, 0xffff0000, v95
	v_and_b32_e32 v99, 0xffff0000, v103
	v_pk_mul_f32 v[96:97], v[96:97], v[98:99]
	s_nop 0
	v_cvt_pk_bf16_f32 v95, v96, v97
	v_add_u32_e32 v96, 0x28000, v116
	v_mov_b32_e32 v97, v2
	v_lshl_add_u64 v[96:97], v[96:97], 1, s[82:83]
	v_add_co_u32_e32 v100, vcc, s3, v96
	s_nop 1
	v_addc_co_u32_e32 v101, vcc, 0, v97, vcc
	ds_read_b128 v[96:99], v246 offset:51712
	global_store_dwordx4 v[100:101], v[92:95], off
	s_cmp_lg_u32 s32, 0
	s_cbranch_scc1 .Lspw6_a
	s_waitcnt vmcnt(7)
	s_branch .Lspw6_j

.Lspw6_j:
	v_lshlrev_b32_e32 v100, 16, v88
	v_and_b32_e32 v101, 0xffff0000, v88
	ds_read_b128 v[92:95], v246 offset:60160
	s_waitcnt lgkmcnt(1)
	v_lshlrev_b32_e32 v102, 16, v96
	v_and_b32_e32 v103, 0xffff0000, v96
	v_pk_mul_f32 v[100:101], v[100:101], v[102:103]
	v_lshlrev_b32_e32 v96, 16, v97
	v_cvt_pk_bf16_f32 v88, v100, v101
	v_lshlrev_b32_e32 v100, 16, v89
	v_and_b32_e32 v101, 0xffff0000, v89
	v_and_b32_e32 v97, 0xffff0000, v97
	v_pk_mul_f32 v[96:97], v[100:101], v[96:97]
	v_lshlrev_b32_e32 v100, 16, v98
	v_cvt_pk_bf16_f32 v89, v96, v97
	v_lshlrev_b32_e32 v96, 16, v90
	v_and_b32_e32 v97, 0xffff0000, v90
	v_and_b32_e32 v101, 0xffff0000, v98
	v_pk_mul_f32 v[96:97], v[96:97], v[100:101]
	v_lshlrev_b32_e32 v98, 16, v99
	v_cvt_pk_bf16_f32 v90, v96, v97
	v_lshlrev_b32_e32 v96, 16, v91
	v_and_b32_e32 v97, 0xffff0000, v91
	v_and_b32_e32 v99, 0xffff0000, v99
	v_pk_mul_f32 v[96:97], v[96:97], v[98:99]
	s_nop 0
	v_cvt_pk_bf16_f32 v91, v96, v97
	v_add_u32_e32 v96, 0x30000, v116
	v_mov_b32_e32 v97, v2
	v_lshl_add_u64 v[96:97], v[96:97], 1, s[82:83]
	v_add_co_u32_e32 v96, vcc, s3, v96
	s_nop 1
	v_addc_co_u32_e32 v97, vcc, 0, v97, vcc
	global_store_dwordx4 v[96:97], v[88:91], off
	s_cmp_lg_u32 s32, 0
	s_cbranch_scc1 .Lspw7_a
	s_waitcnt vmcnt(7)
	s_branch .Lspw7_j

.Lspw7_j:
	s_nop 0
	v_lshlrev_b32_e32 v88, 16, v84
	v_and_b32_e32 v89, 0xffff0000, v84
	s_waitcnt lgkmcnt(0)
	v_lshlrev_b32_e32 v90, 16, v92
	v_and_b32_e32 v91, 0xffff0000, v92
	v_pk_mul_f32 v[88:89], v[88:89], v[90:91]
	v_lshlrev_b32_e32 v90, 16, v93
	v_cvt_pk_bf16_f32 v84, v88, v89
	v_lshlrev_b32_e32 v88, 16, v85
	v_and_b32_e32 v89, 0xffff0000, v85
	v_and_b32_e32 v91, 0xffff0000, v93
	v_pk_mul_f32 v[88:89], v[88:89], v[90:91]
	v_lshlrev_b32_e32 v90, 16, v94
	v_cvt_pk_bf16_f32 v85, v88, v89
	v_lshlrev_b32_e32 v88, 16, v86
	v_and_b32_e32 v89, 0xffff0000, v86
	v_and_b32_e32 v91, 0xffff0000, v94
	v_pk_mul_f32 v[88:89], v[88:89], v[90:91]
	v_lshlrev_b32_e32 v90, 16, v95
	v_cvt_pk_bf16_f32 v86, v88, v89
	v_lshlrev_b32_e32 v88, 16, v87
	v_and_b32_e32 v89, 0xffff0000, v87
	v_and_b32_e32 v91, 0xffff0000, v95
	v_pk_mul_f32 v[88:89], v[88:89], v[90:91]
	s_nop 0
	v_cvt_pk_bf16_f32 v87, v88, v89
	v_add_u32_e32 v88, 0x38000, v116
	v_mov_b32_e32 v89, v2
	v_lshl_add_u64 v[88:89], v[88:89], 1, s[82:83]
	v_add_co_u32_e32 v88, vcc, 0x9900000, v88
	s_nop 1
	v_addc_co_u32_e32 v89, vcc, 0, v89, vcc
	s_andn2_b64 vcc, exec, s[98:99]
	global_store_dwordx4 v[88:89], v[84:87], off
	s_cbranch_vccnz .LBB0_533
	v_mov_b32_e32 v28, v196
	v_mov_b32_e32 v29, v2
	v_lshl_add_u64 v[4:5], v[28:29], 2, s[96:97]
	v_add_u32_e32 v6, 4, v28
	v_mov_b32_e32 v7, v2
	v_add_u32_e32 v12, 0x1000, v28
	v_mov_b32_e32 v13, v2
	v_add_u32_e32 v14, 0x1004, v28
	v_mov_b32_e32 v15, v2
	v_add_u32_e32 v20, 0x2000, v28
	v_mov_b32_e32 v21, v2
	v_add_u32_e32 v22, 0x2004, v28
	v_mov_b32_e32 v23, v2
	v_add_u32_e32 v30, 0x3000, v28
	v_mov_b32_e32 v31, v2
	v_add_u32_e32 v28, 0x3004, v28
	v_lshl_add_u64 v[8:9], v[6:7], 2, s[96:97]
	v_lshl_add_u64 v[12:13], v[12:13], 2, s[96:97]
	v_lshl_add_u64 v[16:17], v[14:15], 2, s[96:97]
	v_lshl_add_u64 v[20:21], v[20:21], 2, s[96:97]
	v_lshl_add_u64 v[24:25], v[22:23], 2, s[96:97]
	v_lshl_add_u64 v[30:31], v[30:31], 2, s[96:97]
	v_lshl_add_u64 v[36:37], v[28:29], 2, s[96:97]
	global_load_dwordx4 v[4:7], v[4:5], off
	s_nop 0
	global_load_dwordx4 v[8:11], v[8:9], off
	s_nop 0
	global_load_dwordx4 v[12:15], v[12:13], off
	s_nop 0
	global_load_dwordx4 v[16:19], v[16:17], off
	s_nop 0
	global_load_dwordx4 v[20:23], v[20:21], off
	s_nop 0
	global_load_dwordx4 v[24:27], v[24:25], off
	s_nop 0
	global_load_dwordx4 v[28:31], v[30:31], off
	s_nop 0
	global_load_dwordx4 v[36:39], v[36:37], off
	s_branch .LBB0_533
